# attention q/k RMS-norm pass moved from P2b (all WGs) to the start of P3 on the 192 non-scan WGs, overlapped with the RWKV scan; release counter + acquire before the attention work
# baseline (speedup 1.0000x reference)
; __device__ __forceinline__ float bflo(unsigned u) { return __uint_as_float(u << 16); }
; __device__ __forceinline__ float bfhi(unsigned u) { return __uint_as_float(u & 0xffff0000u); }
; __device__ __forceinline__ void p2_qknorm_row(const Args& a, int row, int lane) {
;     bf16* zb = (bf16*)(a.ws + WS_ZB) + (size_t)row * 5120;
; #pragma unroll
;     for (int part = 0; part < 2; ++part) {
;         v4u* p = (v4u*)(zb + part * 1024 + lane * 16); const v4u u0 = p[0], u1 = p[1];
;         float x[16];
; #pragma unroll
;         for (int e = 0; e < 4; ++e) { x[2 * e] = bflo(u0[e]); x[2 * e + 1] = bfhi(u0[e]); x[8 + 2 * e] = bflo(u1[e]); x[8 + 2 * e + 1] = bfhi(u1[e]); }
;         float ss = 0.f;
; #pragma unroll
;         for (int e = 0; e < 16; ++e) ss += x[e] * x[e];
;         ss = quad_sum(ss);
;         const float rstd = (1.f / sqrtf(ss * (1.f / 64.f) + RMS_EPS)) * (part == 0 ? attn_body::C2 : 1.f);
;         const f32x4* g4 = (const f32x4*)(a.in[part == 0 ? 19 : 20] + (lane & 3) * 16);
; __global__ void __launch_bounds__(NTHR, 2) hybrid_fwd(Args args) {
;     ...
;         for (int m = F.gw; m < M; m += F.NGW) p2_qknorm_row(args, m, F.lane);
.LBB0_317:
	v_cndmask_b32_e64 v0, 0, 1, s[10:11]
	v_cmp_ne_u32_e64 s[0:1], 1, v0
	s_andn2_b64 vcc, exec, s[10:11]
	v_lshlrev_b32_e32 v0, 4, v10
	v_writelane_b32 v254, s0, 39
	s_nop 1
	v_writelane_b32 v254, s1, 40
	s_nop 0
	v_readlane_b32 s10, v254, 26
	v_readlane_b32 s11, v254, 27
	s_branch .LBB0_320
.Lqk_setup:
	s_mul_i32 s0, s64, 0x2800
	s_mul_hi_i32 s1, s64, 0x2800
	s_add_u32 s0, s90, s0
	v_ashrrev_i32_e32 v1, 31, v0
	v_lshlrev_b32_e32 v2, 6, v10
	v_readlane_b32 s16, v254, 6
	s_addc_u32 s1, s91, s1
	v_and_b32_e32 v4, 0xc0, v2
	v_mov_b32_e32 v5, 0
	v_readlane_b32 s22, v254, 12
	v_readlane_b32 s23, v254, 13
	v_readlane_b32 s24, v254, 14
	v_readlane_b32 s25, v254, 15
	v_lshl_add_u64 v[6:7], v[0:1], 1, s[0:1]
	s_mov_b64 s[0:1], 0xf000000
	v_lshl_add_u64 v[2:3], s[22:23], 0, v[4:5]
	v_lshl_add_u64 v[4:5], s[24:25], 0, v[4:5]
	v_lshl_add_u64 v[6:7], v[6:7], 0, s[0:1]
	s_mul_hi_i32 s1, s10, 0x2800
	s_mul_i32 s0, s10, 0x2800
	v_mov_b32_e32 v1, 0x358637bd
	s_mov_b32 s2, 0xf800000
	v_mov_b32_e32 v12, 0x260
	s_mov_b32 s3, s64
	v_readlane_b32 s17, v254, 7
	v_readlane_b32 s18, v254, 8
	v_readlane_b32 s19, v254, 9
	v_readlane_b32 s20, v254, 10
	v_readlane_b32 s21, v254, 11
	v_readlane_b32 s26, v254, 16
	v_readlane_b32 s27, v254, 17
	v_readlane_b32 s28, v254, 18
	v_readlane_b32 s29, v254, 19
	v_readlane_b32 s30, v254, 20
	v_readlane_b32 s31, v254, 21

; __global__ void __launch_bounds__(NTHR, 2) hybrid_fwd(Args args) {
;     ...
;         for (int m = F.gw; m < M; m += F.NGW) p2_qknorm_row(args, m, F.lane);
;         for (int tile = blockIdx.x; tile < T / 32; tile += F.G) p2_rwprep_tile(F, args, tile * 32); }
.LBB0_320:
	s_cmp_eq_u32 s98, 3
	s_cbranch_scc1 .Lqk_late_done
	s_cmpk_lt_i32 s94, 0x200
	s_cselect_b64 s[0:1], -1, 0
	v_writelane_b32 v254, s0, 41
	s_cmpk_gt_i32 s94, 0x1ff
	s_nop 0
	v_writelane_b32 v254, s1, 42
	s_cbranch_scc1 .LBB0_347
	v_writelane_b32 v255, s36, 8
	v_writelane_b32 v255, s37, 9
	v_writelane_b32 v255, s38, 10
	v_writelane_b32 v255, s39, 11
	v_writelane_b32 v255, s40, 12
	v_writelane_b32 v255, s41, 13
	v_writelane_b32 v255, s42, 14
	v_writelane_b32 v255, s43, 15
	v_writelane_b32 v255, s44, 16
	v_writelane_b32 v255, s45, 17
	v_writelane_b32 v255, s46, 18
	v_writelane_b32 v255, s47, 19
	v_writelane_b32 v255, s48, 20
	v_writelane_b32 v255, s49, 21
	v_writelane_b32 v255, s50, 22
	v_writelane_b32 v255, s51, 23

; __global__ void __launch_bounds__(NTHR, 2) hybrid_fwd(Args args) {
;     ...
;         for (int m = F.gw; m < M; m += F.NGW) p2_qknorm_row(args, m, F.lane);
;     ...
;     {   if ((int)blockIdx.x < NRWB) p3_rwkv_state(F, args);
.Lrw_late_entry:
	s_mov_b32 s98, 3
	v_mov_b32_e32 v206, v64
	s_sub_i32 s64, s94, 64
	s_lshl_b32 s64, s64, 3
	s_add_i32 s64, s64, s92
	s_sub_i32 s10, s97, 64
	s_lshl_b32 s10, s10, 3
	v_mbcnt_lo_u32_b32 v10, -1, 0
	v_mbcnt_hi_u32_b32 v10, -1, v10
	v_lshlrev_b32_e32 v0, 4, v10
	s_branch .Lqk_setup
.Lqk_late_done:
	s_waitcnt vmcnt(0)
	s_barrier
	s_cmp_lg_u32 s92, 0
	s_cbranch_scc1 .Lqk_pub_skip
	buffer_wbl2 sc1
	s_waitcnt vmcnt(0)
	v_mov_b32_e32 v204, 0x8c00
	v_mov_b32_e32 v205, 1
	s_mov_b64 exec, 1
	global_atomic_add v204, v205, s[90:91]
	s_mov_b64 exec, -1
.Lqk_pub_skip:
	v_mov_b32_e32 v64, v206
	v_readlane_b32 s64, v254, 34
	v_readlane_b32 s10, v254, 26
	v_readlane_b32 s11, v254, 27
	s_mov_b32 s98, 1
	v_readlane_b32 s36, v255, 8
	v_readlane_b32 s37, v255, 9
	v_readlane_b32 s38, v255, 10
	v_readlane_b32 s39, v255, 11
	v_readlane_b32 s40, v255, 12
	v_readlane_b32 s41, v255, 13
	v_readlane_b32 s42, v255, 14
	v_readlane_b32 s43, v255, 15
	v_readlane_b32 s44, v255, 16
	v_readlane_b32 s45, v255, 17
	v_readlane_b32 s46, v255, 18
	v_readlane_b32 s47, v255, 19
	v_readlane_b32 s48, v255, 20
	v_readlane_b32 s49, v255, 21
	v_readlane_b32 s50, v255, 22
	v_readlane_b32 s51, v255, 23
	s_add_u32 s6, s90, 0x3300000
	s_addc_u32 s7, s91, 0
	s_add_u32 s8, s90, 0x3380000
	s_addc_u32 s9, s91, 0
	s_add_u32 s14, s90, 0x8000000
	s_addc_u32 s15, s91, 0
	v_mbcnt_lo_u32_b32 v10, -1, 0
	v_mbcnt_hi_u32_b32 v10, -1, v10
	v_and_b32_e32 v11, 15, v10
	v_lshlrev_b32_e32 v0, 4, v10
	s_nop 4
	s_branch .Lrw_again

; __global__ void __launch_bounds__(NTHR, 2) hybrid_fwd(Args args) {
;     ...
;         const attn_body::bf16* ZBq = (const attn_body::bf16*)(ws + WS_ZB); attn_body::bf16* Yo = (attn_body::bf16*)(ws + WS_XN) + 1024; const float* F2 = (const float*)(ws + WS_F2);
;         float gapB; { const float bq = fabsf(args.in[19][F.lane]), bk = fabsf(args.in[20][F.lane]); float mq = bq, mk = bk;
; #pragma unroll
;             for (int o = 1; o < 64; o <<= 1) { mq = fmaxf(mq, __shfl_xor(mq, o)); mk = fmaxf(mk, __shfl_xor(mk, o)); }
;             const float gv_ = 2.f * (64.f * mq * mk * 0.125f * LOG2E * 1.03f) + 48.f; asm volatile("v_readfirstlane_b32 %0, %1" : "=s"(gapB) : "v"(gv_)); }
.LBB0_457:
	s_cmp_lg_u32 s92, 0
	s_cbranch_scc1 .Lqk_wait_done
	s_sub_i32 s101, s97, 64
	v_mov_b32_e32 v204, 0x8c00
.Lqk_poll:
	global_load_dword v205, v204, s[90:91] sc1
	s_waitcnt vmcnt(0)
	v_readfirstlane_b32 s100, v205
	s_cmp_ge_u32 s100, s101
	s_cbranch_scc1 .Lqk_poll_ok
	s_sleep 8
	s_branch .Lqk_poll
.Lqk_poll_ok:
	buffer_inv sc1
	s_waitcnt vmcnt(0)
.Lqk_wait_done:
	s_barrier
	v_writelane_b32 v254, s94, 43
	v_ashrrev_i32_e32 v77, 31, v76
	v_readlane_b32 s0, v254, 6
	v_lshlrev_b64 v[0:1], 2, v[76:77]
	v_readlane_b32 s6, v254, 12
	v_readlane_b32 s7, v254, 13
	v_readlane_b32 s8, v254, 14
	v_readlane_b32 s9, v254, 15
	v_lshl_add_u64 v[2:3], s[6:7], 0, v[0:1]
	global_load_dword v2, v[2:3], off
	v_lshl_add_u64 v[0:1], s[8:9], 0, v[0:1]
	global_load_dword v0, v[0:1], off
	v_readlane_b32 s1, v254, 7
	v_readlane_b32 s0, v254, 2
	v_mbcnt_hi_u32_b32 v3, -1, v156
	v_readlane_b32 s1, v254, 3
	v_and_b32_e32 v5, 64, v3
	v_xor_b32_e32 v6, 1, v3
	v_cndmask_b32_e64 v4, 0, 1, s[0:1]
	v_cmp_ne_u32_e64 s[18:19], 1, v4
	v_add_u32_e32 v4, 64, v5
	v_xor_b32_e32 v7, 2, v3
	v_cmp_lt_i32_e32 vcc, v6, v4
	v_xor_b32_e32 v8, 4, v3
	v_xor_b32_e32 v9, 8, v3
	v_cndmask_b32_e32 v5, v3, v6, vcc
	v_cmp_lt_i32_e32 vcc, v7, v4
	v_xor_b32_e32 v10, 16, v3
	v_xor_b32_e32 v11, 32, v3
	v_cndmask_b32_e32 v6, v3, v7, vcc
	v_cmp_lt_i32_e32 vcc, v8, v4
	v_lshlrev_b32_e32 v200, 2, v5
	v_lshlrev_b32_e32 v201, 2, v6
	v_cndmask_b32_e32 v7, v3, v8, vcc
	v_cmp_lt_i32_e32 vcc, v9, v4
	v_lshlrev_b32_e32 v202, 2, v7
	s_add_u32 s84, s90, 0x4000800
	v_cndmask_b32_e32 v8, v3, v9, vcc
	v_cmp_lt_i32_e32 vcc, v10, v4
	v_lshlrev_b32_e32 v203, 2, v8
	s_addc_u32 s83, s91, 0
	v_cndmask_b32_e32 v9, v3, v10, vcc
	v_cmp_lt_i32_e32 vcc, v11, v4
	s_add_u32 s20, s90, 0x3c00000
	s_addc_u32 s21, s91, 0
	v_cndmask_b32_e32 v3, v3, v11, vcc
	v_lshlrev_b32_e32 v205, 2, v3
	v_lshlrev_b32_e32 v204, 2, v9
	s_add_u32 s0, s90, 0xf000800
	v_readlane_b32 s2, v254, 8
	v_readlane_b32 s3, v254, 9
	v_readlane_b32 s4, v254, 10
	v_readlane_b32 s5, v254, 11
	v_readlane_b32 s10, v254, 16
	v_readlane_b32 s11, v254, 17
	v_readlane_b32 s12, v254, 18
	v_readlane_b32 s13, v254, 19
	v_readlane_b32 s14, v254, 20
	v_readlane_b32 s15, v254, 21
	v_writelane_b32 v254, s0, 44
	s_addc_u32 s0, s91, 0
	v_writelane_b32 v254, s0, 45
	s_add_u32 s0, s90, 0xf001000
	v_writelane_b32 v254, s0, 46
	s_addc_u32 s0, s91, 0
	v_writelane_b32 v254, s0, 47
	s_add_u32 s0, s90, 0xf001800
	v_writelane_b32 v254, s0, 48
	s_addc_u32 s0, s91, 0
	v_writelane_b32 v254, s0, 49
	s_lshl_b32 s0, s92, 5
	v_writelane_b32 v254, s0, 50
	s_lshl_b32 s3, s92, 4
	v_readlane_b32 s0, v254, 25
	s_lshl_b32 s0, s0, 2
	s_lshl_b32 s1, s92, 3
	s_add_i32 s96, s0, 0
	s_and_b32 s0, s3, 48
	s_lshl_b32 s6, s92, 10
	v_writelane_b32 v254, s0, 51
	s_and_b32 s0, s1, 0x1fffffe0
	s_cmp_lg_u32 0, -1
	s_cselect_b32 s3, 0, 0
	s_lshl_b32 s24, s0, 1
	s_add_i32 s0, 0, 0x14a00
	s_lshl_b32 s4, s92, 12
	v_writelane_b32 v254, s0, 52
	s_add_i32 s5, s6, 0
	v_writelane_b32 v254, s6, 2
	s_waitcnt vmcnt(1)
	v_and_b32_e32 v3, 0x7fffffff, v2
	ds_bpermute_b32 v3, v200, v3
	s_waitcnt vmcnt(0)
	v_and_b32_e32 v4, 0x7fffffff, v0
	ds_bpermute_b32 v4, v200, v4
	v_max_f32_e64 v2, |v2|, |v2|
	v_max_f32_e64 v0, |v0|, |v0|
	s_waitcnt lgkmcnt(1)
	v_max_f32_e32 v3, v3, v3
	v_max_f32_e32 v2, v2, v3
	s_waitcnt lgkmcnt(0)
	v_max_f32_e32 v4, v4, v4
	v_max_f32_e32 v0, v0, v4
	ds_bpermute_b32 v3, v201, v2
	ds_bpermute_b32 v4, v201, v0
	s_add_i32 s0, s4, 0
	v_writelane_b32 v254, s0, 53
	s_add_i32 s0, s5, 0x14800
	s_waitcnt lgkmcnt(1)
	v_max_f32_e32 v3, v3, v3
	s_waitcnt lgkmcnt(0)
	v_max_f32_e32 v4, v4, v4
	v_max_f32_e32 v2, v2, v3
	v_max_f32_e32 v0, v0, v4
	ds_bpermute_b32 v3, v202, v2
	ds_bpermute_b32 v4, v202, v0
	s_add_i32 s7, 0, 0x25800
	v_writelane_b32 v254, s0, 54
	s_add_i32 s8, 0, 0x25804
	s_waitcnt lgkmcnt(1)
	v_max_f32_e32 v3, v3, v3
	s_waitcnt lgkmcnt(0)
	v_max_f32_e32 v4, v4, v4
	v_max_f32_e32 v2, v2, v3
	v_max_f32_e32 v0, v0, v4
	ds_bpermute_b32 v3, v203, v2
	ds_bpermute_b32 v4, v203, v0
	v_writelane_b32 v254, s7, 55
	v_writelane_b32 v254, s8, 56
	s_mov_b32 s86, 0xfff60000
	s_waitcnt lgkmcnt(1)
	v_max_f32_e32 v3, v3, v3
	s_waitcnt lgkmcnt(0)
	v_max_f32_e32 v4, v4, v4
	v_max_f32_e32 v2, v2, v3
	v_max_f32_e32 v0, v0, v4
	ds_bpermute_b32 v3, v204, v2
	ds_bpermute_b32 v4, v204, v0
	s_add_i32 s74, s6, s3
	s_mov_b32 s77, 0
	v_mov_b32_e32 v1, 0
	s_waitcnt lgkmcnt(1)
	v_max_f32_e32 v3, v3, v3
	s_waitcnt lgkmcnt(0)
	v_max_f32_e32 v4, v4, v4
	v_max_f32_e32 v2, v2, v3
	v_max_f32_e32 v0, v0, v4
	ds_bpermute_b32 v3, v205, v2
	ds_bpermute_b32 v4, v205, v0
	s_movk_i32 s75, 0x2800
	s_mov_b64 s[80:81], 0x140000
	s_mov_b32 s87, -1
	s_waitcnt lgkmcnt(1)
	v_max_f32_e32 v3, v3, v3
	s_waitcnt lgkmcnt(0)
	v_max_f32_e32 v4, v4, v4
	v_max_f32_e32 v2, v2, v3
	v_max_f32_e32 v0, v0, v4
	v_mul_f32_e32 v2, 0x42800000, v2
	v_mul_f32_e32 v0, v0, v2
	v_mul_f32_e32 v0, 0x3e000000, v0
	v_mul_f32_e32 v0, 0x3fb8aa3b, v0
	v_mul_f32_e32 v0, 0x3f83d70a, v0
	v_fmaak_f32 v0, 2.0, v0, 0x42400000
	v_readfirstlane_b32 s0, v0
	s_mov_b32 s2, 0x41000000
	v_writelane_b32 v254, s0, 57
	v_writelane_b32 v254, s18, 58
	v_mov_b32_e32 v206, 0xff800000
	s_mov_b64 s[92:93], 0x1e0000
	v_writelane_b32 v254, s19, 59
	v_writelane_b32 v254, s20, 60
	v_writelane_b32 v254, s21, 61
	v_writelane_b32 v254, s70, 62
	s_lshl_b32 s22, s1, 1
	v_mov_b32_e32 v207, s7
	v_mov_b32_e32 v208, s8
	s_add_i32 s34, s74, 0x6000
	v_mov_b32_e32 v209, 0xa0000
	v_writelane_b32 v254, s71, 63
	s_branch .LBB0_460
